# al1 + nt hint on the prep loop's once-read P-row loads (18 loads)
# speedup vs baseline: 1.0046x; 1.0005x over previous
.LBB0_330:
	v_lshl_add_u64 v[40:41], s[10:11], 0, v[26:27]
	v_add_co_u32_e32 v0, vcc, 0x19400000, v40
	v_lshl_add_u64 v[30:31], s[10:11], 0, v[22:23]
	s_nop 0
	v_addc_co_u32_e32 v1, vcc, 0, v41, vcc
	v_add_co_u32_e32 v2, vcc, 0x19401000, v40
	v_lshl_add_u64 v[38:39], s[10:11], 0, v[28:29]
	s_nop 0
	v_addc_co_u32_e32 v3, vcc, 0, v41, vcc
	v_add_co_u32_e32 v30, vcc, 0x19401000, v30
	s_mov_b64 s[8:9], 0x19401800
	s_nop 0
	v_addc_co_u32_e32 v31, vcc, 0, v31, vcc
	global_load_dword v52, v[2:3], off offset:2176 nt
	global_load_dword v50, v[2:3], off offset:2688 nt
	global_load_dword v48, v[2:3], off offset:3200 nt
	global_load_dword v47, v[30:31], off offset:1024 nt
	global_load_dword v46, v[30:31], off offset:1280 nt
	global_load_dword v45, v[30:31], off offset:1536 nt
	global_load_dword v44, v[30:31], off offset:1792 nt
	global_load_dword v54, v[2:3], off nt
	global_load_dword v59, v[0:1], off offset:3072 nt
	global_load_dword v58, v[0:1], off offset:3136 nt
	global_load_dword v53, v[38:39], off nt
	global_load_dword v57, v[0:1], off offset:3584 nt
	global_load_dword v56, v[0:1], off offset:3648 nt
	global_load_dword v51, v[38:39], off offset:512 nt
	global_load_dword v49, v[38:39], off offset:1024 nt
	global_load_dword v55, v[38:39], off offset:-2176 nt
	v_lshl_add_u64 v[30:31], s[10:11], 0, v[24:25]
	v_lshl_add_u64 v[32:33], v[30:31], 0, s[8:9]
	v_mov_b32_e32 v37, 0
	v_mov_b32_e32 v34, 0
	v_mov_b32_e32 v35, 0
	s_and_saveexec_b64 s[8:9], s[4:5]
	s_cbranch_execz .LBB0_332
	v_add_co_u32_e32 v0, vcc, 0x19401000, v30
	s_nop 1
	v_addc_co_u32_e32 v1, vcc, 0, v31, vcc
	global_load_ushort v0, v[0:1], off offset:2080 nt
	s_nop 0
	global_load_ushort v1, v[32:33], off nt
	s_waitcnt vmcnt(0)
	v_lshlrev_b32_e32 v34, 16, v0
	v_lshlrev_b32_e32 v35, 16, v1
